# group barriers: L1 invalidate issued after the arrival atomic and first poll load instead of before them (s_sleep 10 polls kept)
# baseline (speedup 1.0000x reference)
; __device__ __forceinline__ unsigned xb_ld(unsigned* p)              { return __hip_atomic_load(p, __ATOMIC_RELAXED, __HIP_MEMORY_SCOPE_AGENT); }
; __device__ __forceinline__ unsigned xb_add(unsigned* p, unsigned v) { return __hip_atomic_fetch_add(p, v, __ATOMIC_RELAXED, __HIP_MEMORY_SCOPE_AGENT); }
; __device__ __forceinline__ void grp_barrier(unsigned* cntw, unsigned* tmo) {
;     asm volatile("s_waitcnt vmcnt(0)" ::: "memory");
;     __syncthreads();
;     if (threadIdx.x == 0) {
;         __builtin_amdgcn_s_waitcnt(0);
;         asm volatile("buffer_inv sc1" ::: "memory");
;         const unsigned old = xb_add(cntw, 1u);
;         const unsigned target = (old / 32u + 1u) * 32u;
;         unsigned sp = 0u;
;         while (xb_ld(cntw) < target) { __builtin_amdgcn_s_sleep(1);
;             if ((++sp & 255u) == 0u) { if (xb_ld(tmo)) break; if (sp > XB_SPIN_CAP) { atomicAdd(tmo, 1u); break; } } }
;         asm volatile("s_waitcnt vmcnt(0)" ::: "memory");
;     }
;     __syncthreads();
.LBB0_453:
	s_cmp_gt_i32 s77, 2
	s_cselect_b64 s[0:1], -1, 0
	s_and_b64 s[2:3], s[14:15], s[0:1]
	v_readlane_b32 s90, v254, 18
	s_andn2_b64 vcc, exec, s[2:3]
	v_readlane_b32 s91, v254, 19
	s_cbranch_vccnz .LBB0_524
	s_cmp_lg_u32 s100, 0
	s_cbranch_scc1 .LBB0_524
	s_add_i32 s2, 0, 0x20170
	v_mov_b32_e32 v2, s2
	ds_read_b32 v2, v2
	s_waitcnt lgkmcnt(0)
	v_cmp_eq_u32_e32 vcc, 0, v2
	s_cbranch_vccnz .LBB0_467
	s_waitcnt vmcnt(0)
	s_barrier
	s_and_saveexec_b64 s[2:3], s[92:93]
	s_cbranch_execz .LBB0_472
	s_lshl_b32 s4, s10, 8
	s_and_b32 s4, s4, 0x700
	s_mov_b64 s[6:7], exec
	s_add_u32 s4, s22, s4
	s_addc_u32 s5, s23, 0
	s_waitcnt vmcnt(0) expcnt(0) lgkmcnt(0)
	v_mbcnt_lo_u32_b32 v2, s6, 0
	s_add_u32 s4, s4, 0x2800
	v_mbcnt_hi_u32_b32 v3, s7, v2
	s_addc_u32 s5, s5, 0
	v_cmp_eq_u32_e32 vcc, 0, v3
	s_and_saveexec_b64 s[8:9], vcc
	s_cbranch_execz .LBB0_458
	s_bcnt1_i32_b64 s6, s[6:7]
	v_mov_b32_e32 v2, 0
	v_mov_b32_e32 v4, s6
	global_atomic_add v4, v2, v4, s[4:5] sc0
.LBB0_458:
	s_or_b64 exec, exec, s[8:9]
	v_mov_b32_e32 v2, 0
	global_load_dword v5, v2, s[4:5] sc1
	buffer_inv sc1
	s_waitcnt vmcnt(1)
	v_readfirstlane_b32 s6, v4
	s_nop 1
	v_add_u32_e32 v3, s6, v3
	v_and_b32_e32 v3, 0xffffffe0, v3
	v_add_u32_e32 v3, 32, v3
	s_waitcnt vmcnt(0)
	v_cmp_lt_u32_e32 vcc, v5, v3
	s_and_saveexec_b64 s[6:7], vcc
	s_cbranch_execz .LBB0_471
	s_add_u32 s8, s22, 0x4200
	s_addc_u32 s9, s23, 0
	s_mov_b32 s11, 1
	s_mov_b64 s[14:15], 0
	s_branch .LBB0_461

; __device__ __forceinline__ unsigned xb_ld(unsigned* p)              { return __hip_atomic_load(p, __ATOMIC_RELAXED, __HIP_MEMORY_SCOPE_AGENT); }
; __device__ __forceinline__ unsigned xb_add(unsigned* p, unsigned v) { return __hip_atomic_fetch_add(p, v, __ATOMIC_RELAXED, __HIP_MEMORY_SCOPE_AGENT); }
; __device__ __forceinline__ void grp_barrier(unsigned* cntw, unsigned* tmo) {
;     asm volatile("s_waitcnt vmcnt(0)" ::: "memory");
;     __syncthreads();
;     if (threadIdx.x == 0) {
;         __builtin_amdgcn_s_waitcnt(0);
;         asm volatile("buffer_inv sc1" ::: "memory");
;         const unsigned old = xb_add(cntw, 1u);
;         const unsigned target = (old / 32u + 1u) * 32u;
;         unsigned sp = 0u;
;         while (xb_ld(cntw) < target) { __builtin_amdgcn_s_sleep(1);
;             if ((++sp & 255u) == 0u) { if (xb_ld(tmo)) break; if (sp > XB_SPIN_CAP) { atomicAdd(tmo, 1u); break; } } }
;         asm volatile("s_waitcnt vmcnt(0)" ::: "memory");
;     }
;     __syncthreads();
.LBB0_659:
	s_cmp_gt_i32 s77, 3
	s_cselect_b64 s[2:3], -1, 0
	s_and_b64 s[0:1], s[24:25], s[2:3]
	s_andn2_b64 vcc, exec, s[0:1]
	s_cbranch_vccnz .LBB0_729
	s_add_i32 s0, 0, 0x20170
	v_mov_b32_e32 v1, s0
	ds_read_b32 v1, v1
	s_waitcnt lgkmcnt(0)
	v_cmp_eq_u32_e32 vcc, 0, v1
	s_cbranch_vccnz .LBB0_673
	s_waitcnt vmcnt(0)
	s_barrier
	s_and_saveexec_b64 s[0:1], s[92:93]
	s_cbranch_execz .LBB0_678
	s_lshl_b32 s4, s10, 8
	s_and_b32 s4, s4, 0x700
	s_mov_b64 s[6:7], exec
	s_add_u32 s4, s22, s4
	s_addc_u32 s5, s23, 0
	s_waitcnt vmcnt(0) expcnt(0) lgkmcnt(0)
	v_mbcnt_lo_u32_b32 v1, s6, 0
	s_add_u32 s4, s4, 0x2800
	v_mbcnt_hi_u32_b32 v2, s7, v1
	s_addc_u32 s5, s5, 0
	v_cmp_eq_u32_e32 vcc, 0, v2
	s_and_saveexec_b64 s[8:9], vcc
	s_cbranch_execz .LBB0_664
	s_bcnt1_i32_b64 s6, s[6:7]
	v_mov_b32_e32 v1, 0
	v_mov_b32_e32 v3, s6
	global_atomic_add v3, v1, v3, s[4:5] sc0
.LBB0_664:
	s_or_b64 exec, exec, s[8:9]
	v_mov_b32_e32 v1, 0
	global_load_dword v4, v1, s[4:5] sc1
	buffer_inv sc1
	s_waitcnt vmcnt(1)
	v_readfirstlane_b32 s6, v3
	s_nop 1
	v_add_u32_e32 v2, s6, v2
	v_and_b32_e32 v2, 0xffffffe0, v2
	v_add_u32_e32 v2, 32, v2
	s_waitcnt vmcnt(0)
	v_cmp_lt_u32_e32 vcc, v4, v2
	s_and_saveexec_b64 s[6:7], vcc
	s_cbranch_execz .LBB0_677
	s_add_u32 s8, s22, 0x4200
	s_addc_u32 s9, s23, 0
	s_mov_b32 s11, 1
	s_mov_b64 s[16:17], 0
	s_branch .LBB0_667

; __device__ __forceinline__ unsigned xb_ld(unsigned* p)              { return __hip_atomic_load(p, __ATOMIC_RELAXED, __HIP_MEMORY_SCOPE_AGENT); }
; __device__ __forceinline__ unsigned xb_add(unsigned* p, unsigned v) { return __hip_atomic_fetch_add(p, v, __ATOMIC_RELAXED, __HIP_MEMORY_SCOPE_AGENT); }
; __device__ __forceinline__ void grp_barrier(unsigned* cntw, unsigned* tmo) {
;     asm volatile("s_waitcnt vmcnt(0)" ::: "memory");
;     __syncthreads();
;     if (threadIdx.x == 0) {
;         __builtin_amdgcn_s_waitcnt(0);
;         asm volatile("buffer_inv sc1" ::: "memory");
;         const unsigned old = xb_add(cntw, 1u);
;         const unsigned target = (old / 32u + 1u) * 32u;
;         unsigned sp = 0u;
;         while (xb_ld(cntw) < target) { __builtin_amdgcn_s_sleep(1);
;             if ((++sp & 255u) == 0u) { if (xb_ld(tmo)) break; if (sp > XB_SPIN_CAP) { atomicAdd(tmo, 1u); break; } } }
;         asm volatile("s_waitcnt vmcnt(0)" ::: "memory");
;     }
;     __syncthreads();
.LBB0_894:
	s_cmp_gt_i32 s77, 5
	s_cselect_b64 s[0:1], -1, 0
	s_and_b64 s[2:3], s[16:17], s[0:1]
	s_andn2_b64 vcc, exec, s[2:3]
	s_cbranch_vccnz .LBB0_964
	s_add_i32 s2, 0, 0x20170
	v_mov_b32_e32 v1, s2
	ds_read_b32 v1, v1
	s_waitcnt lgkmcnt(0)
	v_cmp_eq_u32_e32 vcc, 0, v1
	s_cbranch_vccnz .LBB0_908
	s_waitcnt vmcnt(0)
	s_barrier
	s_and_saveexec_b64 s[2:3], s[92:93]
	s_cbranch_execz .LBB0_913
	s_lshl_b32 s4, s10, 8
	s_and_b32 s4, s4, 0x700
	s_mov_b64 s[6:7], exec
	s_add_u32 s4, s22, s4
	s_addc_u32 s5, s23, 0
	s_waitcnt vmcnt(0) expcnt(0) lgkmcnt(0)
	v_mbcnt_lo_u32_b32 v1, s6, 0
	s_add_u32 s4, s4, 0x2800
	v_mbcnt_hi_u32_b32 v2, s7, v1
	s_addc_u32 s5, s5, 0
	v_cmp_eq_u32_e32 vcc, 0, v2
	s_and_saveexec_b64 s[8:9], vcc
	s_cbranch_execz .LBB0_899
	s_bcnt1_i32_b64 s6, s[6:7]
	v_mov_b32_e32 v1, 0
	v_mov_b32_e32 v3, s6
	global_atomic_add v3, v1, v3, s[4:5] sc0
.LBB0_899:
	s_or_b64 exec, exec, s[8:9]
	v_mov_b32_e32 v1, 0
	global_load_dword v4, v1, s[4:5] sc1
	buffer_inv sc1
	s_waitcnt vmcnt(1)
	v_readfirstlane_b32 s6, v3
	s_nop 1
	v_add_u32_e32 v2, s6, v2
	v_and_b32_e32 v2, 0xffffffe0, v2
	v_add_u32_e32 v2, 32, v2
	s_waitcnt vmcnt(0)
	v_cmp_lt_u32_e32 vcc, v4, v2
	s_and_saveexec_b64 s[6:7], vcc
	s_cbranch_execz .LBB0_912
	s_add_u32 s8, s22, 0x4200
	s_addc_u32 s9, s23, 0
	s_mov_b32 s28, 1
	s_mov_b64 s[14:15], 0
	s_branch .LBB0_902

; __device__ __forceinline__ unsigned xb_add(unsigned* p, unsigned v) { return __hip_atomic_fetch_add(p, v, __ATOMIC_RELAXED, __HIP_MEMORY_SCOPE_AGENT); }
; __device__ __forceinline__ void grp_barrier(unsigned* cntw, unsigned* tmo) {
;     asm volatile("s_waitcnt vmcnt(0)" ::: "memory");
;     __syncthreads();
;     if (threadIdx.x == 0) {
;         __builtin_amdgcn_s_waitcnt(0);
;         asm volatile("buffer_inv sc1" ::: "memory");
;         const unsigned old = xb_add(cntw, 1u);
;         const unsigned target = (old / 32u + 1u) * 32u;
.LBB0_1021:
	s_cmp_gt_i32 s77, 6
	s_cselect_b64 s[2:3], -1, 0
	s_and_b64 s[0:1], s[0:1], s[2:3]
	s_andn2_b64 vcc, exec, s[0:1]
	s_cbranch_vccnz .LBB0_1091
	s_add_i32 s0, 0, 0x20170
	v_mov_b32_e32 v1, s0
	ds_read_b32 v1, v1
	s_waitcnt lgkmcnt(0)
	v_cmp_eq_u32_e32 vcc, 0, v1
	s_cbranch_vccnz .LBB0_1035
	s_waitcnt vmcnt(0)
	s_barrier
	s_and_saveexec_b64 s[0:1], s[92:93]
	s_cbranch_execz .LBB0_1040
	s_lshl_b32 s4, s10, 8
	s_and_b32 s4, s4, 0x700
	s_mov_b64 s[6:7], exec
	s_add_u32 s4, s22, s4
	s_addc_u32 s5, s23, 0
	s_waitcnt vmcnt(0) expcnt(0) lgkmcnt(0)
	v_mbcnt_lo_u32_b32 v1, s6, 0
	s_add_u32 s4, s4, 0x2800
	v_mbcnt_hi_u32_b32 v2, s7, v1
	s_addc_u32 s5, s5, 0
	v_cmp_eq_u32_e32 vcc, 0, v2
	s_and_saveexec_b64 s[8:9], vcc
	s_cbranch_execz .LBB0_1026
	s_bcnt1_i32_b64 s6, s[6:7]
	v_mov_b32_e32 v1, 0
	v_mov_b32_e32 v3, s6
	global_atomic_add v3, v1, v3, s[4:5] sc0
